# P7: the 8 workgroups that carry a 5th out-GEMM unit skip the ple-proj GEMM (its units spread over the other 248)
# speedup vs baseline: 1.0092x; 1.0092x over previous
.LBB0_1387:
	s_or_b64 exec, exec, s[36:37]
	s_waitcnt lgkmcnt(0)
	s_barrier
	s_mov_b32 s100, s93
	s_mov_b32 s101, s62
	s_cmpk_lg_i32 s93, 0x100
	s_cbranch_scc1 .Lp7_noremap
	s_movk_i32 s100, 0xf8
	s_sub_i32 s101, s62, 8
	s_cmp_lt_u32 s62, 8
	s_cselect_b32 s101, 0x408, s101
.Lp7_noremap:
	v_mov_b32_e32 v2, v228
	s_cmpk_lt_i32 s101, 0x408
	s_cselect_b64 s[4:5], -1, 0
	s_cmpk_gt_i32 s101, 0x407
	v_readfirstlane_b32 s6, v2
	s_cbranch_scc1 .LBB0_1401
	v_bfe_i32 v4, v2, 27, 1
	v_lshlrev_b32_e32 v3, 4, v2
	v_lshrrev_b32_e32 v4, 22, v4
	v_add_u32_e32 v4, v3, v4
	v_and_b32_e32 v4, 0xfffffc00, v4
	v_sub_u32_e32 v4, v3, v4
	v_ashrrev_i32_e32 v0, 31, v2
	v_lshrrev_b32_e32 v5, 4, v4
	v_lshrrev_b32_e32 v0, 26, v0
	v_bitop3_b32 v5, v5, v4, 32 bitop3:0x6c
	v_ashrrev_i32_e32 v4, 31, v4
	v_add_u32_e32 v0, v2, v0
	v_lshrrev_b32_e32 v4, 26, v4
	v_ashrrev_i32_e32 v0, 6, v0
	v_add_u32_e32 v4, v5, v4
	v_lshlrev_b32_e32 v6, 3, v0
	v_ashrrev_i32_e32 v4, 6, v4
	v_and_b32_e32 v6, -16, v6
	v_mul_i32_i24_e32 v7, 64, v4
	v_add_u32_e32 v6, v4, v6
	v_sub_u32_e32 v5, v5, v7
	v_mov_b32_e32 v9, 1
	v_lshlrev_b32_e32 v0, 5, v0
	v_ashrrev_i16_sdwa v5, v9, sext(v5) dst_sel:DWORD dst_unused:UNUSED_PAD src0_sel:DWORD src1_sel:BYTE_0
	v_lshlrev_b32_e32 v7, 1, v6
	v_lshrrev_b32_e32 v8, 2, v6
	v_and_b32_e32 v4, 3, v4
	s_mov_b32 s0, 0x7fffe0
	v_and_b32_e32 v0, 32, v0
	v_bfe_i32 v5, v5, 0, 16
	v_and_b32_e32 v7, 24, v7
	v_and_b32_e32 v8, 4, v8
	v_and_or_b32 v4, v6, s0, v4
	v_or3_b32 v4, v4, v8, v7
	v_add_lshl_u32 v5, v0, v5, 1
	v_add_u32_e32 v3, 0x2000, v3
	v_lshl_add_u32 v130, v4, 9, v5
	v_ashrrev_i32_e32 v4, 31, v3
	v_lshrrev_b32_e32 v4, 22, v4
	v_add_u32_e32 v4, v3, v4
	v_ashrrev_i32_e32 v4, 10, v4
	v_lshl_add_u32 v0, v6, 9, v5
	v_mul_i32_i24_e32 v5, 0x400, v4
	v_sub_u32_e32 v3, v3, v5
	v_lshrrev_b32_e32 v5, 4, v3
	v_bitop3_b32 v3, v5, v3, 32 bitop3:0x6c
	v_ashrrev_i32_e32 v6, 31, v3
	v_lshrrev_b32_e32 v6, 26, v6
	v_lshlrev_b32_e32 v5, 3, v4
	v_add_u32_e32 v6, v3, v6
	v_and_b32_e32 v5, -16, v5
	v_ashrrev_i32_e32 v7, 6, v6
	v_add_u32_e32 v5, v7, v5
	v_and_b32_e32 v7, 3, v7
	v_and_or_b32 v7, v5, s0, v7
	s_ashr_i32 s0, s101, 31
	s_lshr_b32 s0, s0, 30
	s_add_i32 s0, s101, s0
	s_ashr_i32 s8, s6, 6
	s_ashr_i32 s20, s0, 2
	s_and_b32 s0, s0, -4
	s_ashr_i32 s7, s6, 8
	s_lshl_b32 s28, s8, 10
	s_sub_i32 s18, s101, s0
	s_add_u32 s29, s76, 0x32aba000
	s_addc_u32 s30, s77, 0
	s_ashr_i32 s21, s20, 31
	s_lshl_b64 s[0:1], s[20:21], 17
	s_add_u32 s24, s29, s0
	s_addc_u32 s25, s30, s1
	v_readlane_b32 s0, v255, 44
	s_add_u32 s0, s76, s0
	s_addc_u32 s1, s77, 0
	s_add_u32 s21, s0, 0x11c0000
	s_addc_u32 s31, s1, 0
	s_ashr_i32 s19, s18, 31
	v_and_b32_e32 v6, 0xc0, v6
	s_lshl_b64 s[0:1], s[18:19], 17
	v_sub_u32_e32 v3, v3, v6
	s_add_u32 s26, s21, s0
	v_lshlrev_b32_e32 v4, 5, v4
	v_ashrrev_i16_sdwa v3, v9, sext(v3) dst_sel:DWORD dst_unused:UNUSED_PAD src0_sel:DWORD src1_sel:BYTE_0
	v_lshlrev_b32_e32 v6, 1, v5
	v_lshrrev_b32_e32 v8, 2, v5
	s_addc_u32 s27, s31, s1
	s_add_i32 s19, s28, 0
	v_and_b32_e32 v4, 32, v4
	v_bfe_i32 v3, v3, 0, 16
	v_and_b32_e32 v6, 24, v6
	v_and_b32_e32 v8, 4, v8
	s_add_i32 m0, s19, 0x10000
	v_or3_b32 v6, v7, v8, v6
	v_add_lshl_u32 v3, v4, v3, 1
	global_load_lds_dwordx4 v130, s[26:27]
	s_add_i32 m0, s19, 0x12000
	v_lshl_add_u32 v134, v6, 9, v3
	s_add_u32 s0, s26, 0x10000
	global_load_lds_dwordx4 v134, s[26:27]
	s_addc_u32 s1, s27, 0
	s_add_i32 m0, s19, 0x14000
	s_add_i32 s34, s19, 0x2000
	global_load_lds_dwordx4 v130, s[0:1]
	s_add_i32 m0, s19, 0x16000
	v_lshl_add_u32 v132, v5, 9, v3
	global_load_lds_dwordx4 v134, s[0:1]
	s_mov_b32 m0, s19
	s_add_u32 s0, s24, 0x10000
	global_load_lds_dwordx4 v0, s[24:25]
	s_mov_b32 m0, s34
	s_addc_u32 s1, s25, 0
	s_add_i32 s35, s19, 0x4000
	global_load_lds_dwordx4 v132, s[24:25]
	s_mov_b32 m0, s35
	s_add_i32 s36, s19, 0x6000
	global_load_lds_dwordx4 v0, s[0:1]
	s_mov_b32 m0, s36
	s_cmp_eq_u32 s7, 1
	global_load_lds_dwordx4 v132, s[0:1]
	s_cselect_b64 s[0:1], -1, 0
	s_cmp_lg_u32 s7, 1
	s_cbranch_scc1 .LBB0_1390
	s_barrier
.LBB0_1390:
	v_and_b32_e32 v3, 15, v2
	v_and_b32_e32 v12, 48, v2
	v_lshlrev_b32_e32 v3, 6, v3
	v_lshlrev_b32_e32 v2, 2, v2
	v_or_b32_e32 v13, v3, v12
	s_lshl_b32 s7, s7, 13
	v_and_b32_e32 v2, 32, v2
	v_mov_b32_e32 v131, v1
	v_bitop3_b32 v3, v3, v2, v12 bitop3:0x36
	v_bitop3_b32 v12, v13, s7, v2 bitop3:0xde
	s_lshl_b32 s7, s8, 12
	v_lshl_add_u64 v[4:5], s[26:27], 0, v[130:131]
	v_mov_b32_e32 v135, v1
	s_and_b32 s7, s7, 0x3000
	v_lshl_add_u64 v[6:7], s[26:27], 0, v[134:135]
	v_or_b32_e32 v136, s7, v3
	s_add_i32 m0, s19, 0x18000
	v_lshl_add_u64 v[2:3], v[4:5], 0, s[70:71]
	v_lshl_add_u64 v[8:9], s[24:25], 0, v[0:1]
	v_mov_b32_e32 v133, v1
	s_waitcnt vmcnt(2)
	s_barrier
	global_load_lds_dwordx4 v[2:3], off
	v_lshl_add_u64 v[2:3], v[6:7], 0, s[70:71]
	s_add_i32 m0, s19, 0x1a000
	s_add_i32 s37, s19, 0x8000
	s_add_i32 s38, s19, 0xa000
	v_lshl_add_u64 v[10:11], s[24:25], 0, v[132:133]
	global_load_lds_dwordx4 v[2:3], off
	v_lshl_add_u64 v[2:3], v[8:9], 0, s[70:71]
	s_mov_b32 m0, s37
	s_add_u32 s8, s26, 0x10080
	global_load_lds_dwordx4 v[2:3], off
	v_lshl_add_u64 v[2:3], v[10:11], 0, s[70:71]
	s_mov_b32 m0, s38
	s_addc_u32 s9, s27, 0
	global_load_lds_dwordx4 v[2:3], off
	s_add_i32 m0, s19, 0x1c000
	v_lshl_add_u64 v[2:3], s[8:9], 0, v[130:131]
	global_load_lds_dwordx4 v[2:3], off
	v_lshl_add_u64 v[2:3], s[8:9], 0, v[134:135]
	s_add_i32 m0, s19, 0x1e000
	s_cmpk_lt_u32 s6, 0x100
	global_load_lds_dwordx4 v[2:3], off
	s_waitcnt vmcnt(6)
	s_cselect_b64 s[8:9], -1, 0
	s_add_i32 s39, s100, s101
	v_add_u32_e32 v137, 0, v12
	s_mov_b64 s[16:17], s[26:27]
	s_mov_b64 s[14:15], s[24:25]
	s_barrier
	s_branch .LBB0_1393
.LBB0_1391:
	s_add_i32 s39, s39, s100
	s_mov_b64 s[6:7], 0

.LBB0_1401:
	s_cmpk_lt_i32 s62, 0x408
	s_cselect_b64 s[4:5], -1, 0
	s_bitcmp1_b32 s62, 0
	s_cselect_b64 s[0:1], -1, 0
	s_and_b64 vcc, exec, s[0:1]
	s_cbranch_vccz .LBB0_1404
	s_cmp_lt_u32 s62, 8
	s_cbranch_scc1 .LBB0_1404
	s_mov_b32 s0, 4
	s_cmp_lt_i32 s0, 1
	s_cbranch_scc1 .LBB0_1404
